# prep: weight-transpose tile loop software-pipelined (next tile's two 16B loads issued before the current tile's LDS transpose; counted vmcnt(2/3); global loads/stores) on top of v20
# baseline (speedup 1.0000x reference)
.LBB0_8:
	s_cmpk_gt_i32 s53, 0x67f
	s_cbranch_scc0 .Ltp0_F
	s_cmpk_gt_u32 s53, 0x7bf
	s_cbranch_scc0 .Ltp0_E
	s_cmpk_gt_u32 s53, 0x8bf
	s_cbranch_scc0 .Ltp0_D
	s_cmpk_gt_u32 s53, 0x9bf
	s_cbranch_scc0 .Ltp0_C
	s_cmpk_gt_u32 s53, 0xf3f
	s_cbranch_scc0 .Ltp0_B
	s_and_b32 s4, s50, 0x7fffffc0
	s_addk_i32 s4, 0xc300
	s_and_b32 s33, s3, 0x3c0
	s_lshl_b32 s28, s33, 2
	v_or_b32_e32 v24, s4, v1
	v_mov_b32_e32 v25, v3
	v_lshl_add_u64 v[28:29], v[4:5], 0, s[28:29]
	v_lshlrev_b64 v[24:25], 12, v[24:25]
	v_lshl_add_u64 v[24:25], v[28:29], 0, v[24:25]
	v_add_u32_e32 v30, s4, v16
	v_mov_b32_e32 v31, v3
	global_load_dwordx4 v[24:27], v[24:25], off
	v_lshlrev_b64 v[30:31], 12, v[30:31]
	v_lshl_add_u64 v[28:29], v[28:29], 0, v[30:31]
	global_load_dwordx4 v[28:31], v[28:29], off
	v_add_u32_e32 v23, s33, v17
	v_mul_u32_u24_e32 v23, 0xb00, v23
	v_mov_b32_e32 v33, v3
	v_lshlrev_b32_e32 v32, 1, v23
	s_mov_b32 s5, s29
	v_lshl_add_u64 v[32:33], s[30:31], 0, v[32:33]
	v_lshl_add_u64 v[32:33], s[4:5], 1, v[32:33]
	v_lshl_add_u64 v[32:33], v[32:33], 0, v[2:3]
	s_branch .Ltp0_J
.Ltp0_B:
	s_add_i32 s4, s53, 0xf640
	s_and_b32 s5, s4, 0xffff
	s_mul_i32 s5, s5, 0xba2f
	s_lshr_b32 s28, s5, 16
	s_lshr_b32 s5, s5, 22
	s_mulk_i32 s5, 0x58
	s_sub_i32 s4, s4, s5
	s_and_b32 s5, s28, 0xffc0
	s_lshl_b32 s4, s4, 6
	s_and_b32 s4, s4, 0xffc0
	v_or_b32_e32 v23, s5, v1
	s_lshl_b32 s28, s4, 2
	v_mul_u32_u24_e32 v23, 0x1600, v23
	v_lshl_add_u64 v[28:29], v[6:7], 0, s[28:29]
	v_lshlrev_b32_e32 v24, 2, v23
	v_mov_b32_e32 v25, v3
	v_add_u32_e32 v23, s5, v16
	v_lshl_add_u64 v[24:25], v[28:29], 0, v[24:25]
	v_mul_u32_u24_e32 v23, 0x1600, v23
	global_load_dwordx4 v[24:27], v[24:25], off
	v_lshlrev_b32_e32 v30, 2, v23
	v_mov_b32_e32 v31, v3
	v_lshl_add_u64 v[28:29], v[28:29], 0, v[30:31]
	global_load_dwordx4 v[28:31], v[28:29], off
	v_mov_b32_e32 v33, v3
	v_add_lshl_u32 v32, v17, s4, 11
	v_lshl_add_u64 v[32:33], s[34:35], 0, v[32:33]
	s_lshl_b32 s28, s5, 1
	v_lshl_add_u64 v[32:33], v[32:33], 0, s[28:29]
	v_lshl_add_u64 v[32:33], v[32:33], 0, v[2:3]
	s_branch .Ltp0_J
.Ltp0_C:
	s_and_b32 s4, s50, 0x3fc0
	s_addk_i32 s4, 0xdd00
	s_and_b32 s33, s3, 0x3c0
	s_lshl_b32 s28, s33, 2
	v_or_b32_e32 v24, s4, v1
	v_mov_b32_e32 v25, v3
	v_lshl_add_u64 v[28:29], v[8:9], 0, s[28:29]
	v_lshlrev_b64 v[24:25], 12, v[24:25]
	v_lshl_add_u64 v[24:25], v[28:29], 0, v[24:25]
	v_add_u32_e32 v30, s4, v16
	v_mov_b32_e32 v31, v3
	global_load_dwordx4 v[24:27], v[24:25], off
	v_lshlrev_b64 v[30:31], 12, v[30:31]
	v_lshl_add_u64 v[28:29], v[28:29], 0, v[30:31]
	global_load_dwordx4 v[28:31], v[28:29], off
	v_mov_b32_e32 v33, v3
	v_add_lshl_u32 v32, s33, v17, 11
	s_mov_b32 s5, s29
	v_lshl_add_u64 v[32:33], s[36:37], 0, v[32:33]
	v_lshl_add_u64 v[32:33], s[4:5], 1, v[32:33]
	v_lshl_add_u64 v[32:33], v[32:33], 0, v[2:3]
	s_branch .Ltp0_J
.Ltp0_D:
	s_and_b32 s4, s50, 0x3fc0
	s_addk_i32 s4, 0xe100
	s_and_b32 s33, s3, 0x3c0
	s_lshl_b32 s28, s33, 2
	v_or_b32_e32 v24, s4, v1
	v_mov_b32_e32 v25, v3
	v_lshl_add_u64 v[28:29], v[10:11], 0, s[28:29]
	v_lshlrev_b64 v[24:25], 12, v[24:25]
	v_lshl_add_u64 v[24:25], v[28:29], 0, v[24:25]
	v_add_u32_e32 v30, s4, v16
	v_mov_b32_e32 v31, v3
	global_load_dwordx4 v[24:27], v[24:25], off
	v_lshlrev_b64 v[30:31], 12, v[30:31]
	v_lshl_add_u64 v[28:29], v[28:29], 0, v[30:31]
	global_load_dwordx4 v[28:31], v[28:29], off
	v_add_u32_e32 v23, s33, v17
	v_mul_u32_u24_e32 v23, 0x900, v23
	v_mov_b32_e32 v33, v3
	v_lshlrev_b32_e32 v32, 1, v23
	s_mov_b32 s5, s29
	v_lshl_add_u64 v[32:33], s[6:7], 0, v[32:33]
	v_lshl_add_u64 v[32:33], s[4:5], 1, v[32:33]
	v_lshl_add_u64 v[32:33], v[32:33], 0, v[2:3]
	v_add_co_u32_e32 v32, vcc, 0xf80a00, v32
	s_nop 1
	v_addc_co_u32_e32 v33, vcc, 0, v33, vcc
	s_branch .Ltp0_J
.Ltp0_E:
	s_and_b32 s4, s50, 0x1fc0
	s_addk_i32 s4, 0xe600
	s_and_b32 s33, s3, 0x3c0
	s_lshl_b32 s28, s33, 2
	v_or_b32_e32 v24, s4, v1
	v_mov_b32_e32 v25, v3
	v_lshl_add_u64 v[28:29], v[12:13], 0, s[28:29]
	v_lshlrev_b64 v[24:25], 12, v[24:25]
	v_lshl_add_u64 v[24:25], v[28:29], 0, v[24:25]
	v_add_u32_e32 v30, s4, v16
	v_mov_b32_e32 v31, v3
	global_load_dwordx4 v[24:27], v[24:25], off
	v_lshlrev_b64 v[30:31], 12, v[30:31]
	v_lshl_add_u64 v[28:29], v[28:29], 0, v[30:31]
	global_load_dwordx4 v[28:31], v[28:29], off
	v_add_u32_e32 v23, s33, v17
	v_mul_u32_u24_e32 v23, 0x900, v23
	v_mov_b32_e32 v33, v3
	v_lshlrev_b32_e32 v32, 1, v23
	s_mov_b32 s5, s29
	v_lshl_add_u64 v[32:33], s[46:47], 0, v[32:33]
	v_lshl_add_u64 v[32:33], s[4:5], 1, v[32:33]
	v_lshl_add_u64 v[32:33], v[32:33], 0, v[2:3]
	s_branch .Ltp0_J
.Ltp0_F:
	s_mul_hi_i32 s4, s53, 0x4ec4ec4f
	s_lshr_b32 s5, s4, 31
	s_ashr_i32 s4, s4, 5
	s_add_i32 s5, s4, s5
	s_lshl_b32 s4, s5, 6
	s_mulk_i32 s5, 0xe600
	s_add_i32 s44, s3, s5
	s_ashr_i32 s45, s44, 31
	v_lshl_add_u64 v[28:29], s[44:45], 2, v[14:15]
	v_or_b32_e32 v23, s4, v1
	v_mad_i64_i32 v[24:25], s[48:49], v23, s52, v[28:29]
	global_load_dwordx4 v[24:27], v[24:25], off
	v_add_u32_e32 v23, s4, v16
	v_mad_i64_i32 v[28:29], s[48:49], v23, s52, v[28:29]
	global_load_dwordx4 v[28:31], v[28:29], off
	v_add_u32_e32 v32, s44, v17
	v_ashrrev_i32_e32 v33, 31, v32
	v_lshlrev_b64 v[32:33], 11, v[32:33]
	s_ashr_i32 s5, s4, 31
	v_lshl_add_u64 v[32:33], s[6:7], 0, v[32:33]
	v_lshl_add_u64 v[32:33], s[4:5], 1, v[32:33]
	v_lshl_add_u64 v[32:33], v[32:33], 0, v[2:3]
.Ltp0_J:
	s_add_i32 s53, s53, s38
	s_add_i32 s3, s3, s39
	s_add_i32 s50, s50, s51
	s_cmpk_gt_i32 s53, 0x11ff
	s_cbranch_scc1 .Ltp_endA
	s_cmpk_gt_i32 s53, 0x67f
	s_cbranch_scc0 .Ltp1_F
	s_cmpk_gt_u32 s53, 0x7bf
	s_cbranch_scc0 .Ltp1_E
	s_cmpk_gt_u32 s53, 0x8bf
	s_cbranch_scc0 .Ltp1_D
	s_cmpk_gt_u32 s53, 0x9bf
	s_cbranch_scc0 .Ltp1_C
	s_cmpk_gt_u32 s53, 0xf3f
	s_cbranch_scc0 .Ltp1_B
	s_and_b32 s4, s50, 0x7fffffc0
	s_addk_i32 s4, 0xc300
	s_and_b32 s33, s3, 0x3c0
	s_lshl_b32 s28, s33, 2
	v_or_b32_e32 v60, s4, v1
	v_mov_b32_e32 v61, v3
	v_lshl_add_u64 v[64:65], v[4:5], 0, s[28:29]
	v_lshlrev_b64 v[60:61], 12, v[60:61]
	v_lshl_add_u64 v[60:61], v[64:65], 0, v[60:61]
	v_add_u32_e32 v66, s4, v16
	v_mov_b32_e32 v67, v3
	global_load_dwordx4 v[60:63], v[60:61], off
	v_lshlrev_b64 v[66:67], 12, v[66:67]
	v_lshl_add_u64 v[64:65], v[64:65], 0, v[66:67]
	global_load_dwordx4 v[64:67], v[64:65], off
	v_add_u32_e32 v59, s33, v17
	v_mul_u32_u24_e32 v59, 0xb00, v59
	v_mov_b32_e32 v69, v3
	v_lshlrev_b32_e32 v68, 1, v59
	s_mov_b32 s5, s29
	v_lshl_add_u64 v[68:69], s[30:31], 0, v[68:69]
	v_lshl_add_u64 v[68:69], s[4:5], 1, v[68:69]
	v_lshl_add_u64 v[68:69], v[68:69], 0, v[2:3]
	s_branch .Ltp1_J
.Ltp1_B:
	s_add_i32 s4, s53, 0xf640
	s_and_b32 s5, s4, 0xffff
	s_mul_i32 s5, s5, 0xba2f
	s_lshr_b32 s28, s5, 16
	s_lshr_b32 s5, s5, 22
	s_mulk_i32 s5, 0x58
	s_sub_i32 s4, s4, s5
	s_and_b32 s5, s28, 0xffc0
	s_lshl_b32 s4, s4, 6
	s_and_b32 s4, s4, 0xffc0
	v_or_b32_e32 v59, s5, v1
	s_lshl_b32 s28, s4, 2
	v_mul_u32_u24_e32 v59, 0x1600, v59
	v_lshl_add_u64 v[64:65], v[6:7], 0, s[28:29]
	v_lshlrev_b32_e32 v60, 2, v59
	v_mov_b32_e32 v61, v3
	v_add_u32_e32 v59, s5, v16
	v_lshl_add_u64 v[60:61], v[64:65], 0, v[60:61]
	v_mul_u32_u24_e32 v59, 0x1600, v59
	global_load_dwordx4 v[60:63], v[60:61], off
	v_lshlrev_b32_e32 v66, 2, v59
	v_mov_b32_e32 v67, v3
	v_lshl_add_u64 v[64:65], v[64:65], 0, v[66:67]
	global_load_dwordx4 v[64:67], v[64:65], off
	v_mov_b32_e32 v69, v3
	v_add_lshl_u32 v68, v17, s4, 11
	v_lshl_add_u64 v[68:69], s[34:35], 0, v[68:69]
	s_lshl_b32 s28, s5, 1
	v_lshl_add_u64 v[68:69], v[68:69], 0, s[28:29]
	v_lshl_add_u64 v[68:69], v[68:69], 0, v[2:3]
	s_branch .Ltp1_J
.Ltp1_C:
	s_and_b32 s4, s50, 0x3fc0
	s_addk_i32 s4, 0xdd00
	s_and_b32 s33, s3, 0x3c0
	s_lshl_b32 s28, s33, 2
	v_or_b32_e32 v60, s4, v1
	v_mov_b32_e32 v61, v3
	v_lshl_add_u64 v[64:65], v[8:9], 0, s[28:29]
	v_lshlrev_b64 v[60:61], 12, v[60:61]
	v_lshl_add_u64 v[60:61], v[64:65], 0, v[60:61]
	v_add_u32_e32 v66, s4, v16
	v_mov_b32_e32 v67, v3
	global_load_dwordx4 v[60:63], v[60:61], off
	v_lshlrev_b64 v[66:67], 12, v[66:67]
	v_lshl_add_u64 v[64:65], v[64:65], 0, v[66:67]
	global_load_dwordx4 v[64:67], v[64:65], off
	v_mov_b32_e32 v69, v3
	v_add_lshl_u32 v68, s33, v17, 11
	s_mov_b32 s5, s29
	v_lshl_add_u64 v[68:69], s[36:37], 0, v[68:69]
	v_lshl_add_u64 v[68:69], s[4:5], 1, v[68:69]
	v_lshl_add_u64 v[68:69], v[68:69], 0, v[2:3]
	s_branch .Ltp1_J
.Ltp1_D:
	s_and_b32 s4, s50, 0x3fc0
	s_addk_i32 s4, 0xe100
	s_and_b32 s33, s3, 0x3c0
	s_lshl_b32 s28, s33, 2
	v_or_b32_e32 v60, s4, v1
	v_mov_b32_e32 v61, v3
	v_lshl_add_u64 v[64:65], v[10:11], 0, s[28:29]
	v_lshlrev_b64 v[60:61], 12, v[60:61]
	v_lshl_add_u64 v[60:61], v[64:65], 0, v[60:61]
	v_add_u32_e32 v66, s4, v16
	v_mov_b32_e32 v67, v3
	global_load_dwordx4 v[60:63], v[60:61], off
	v_lshlrev_b64 v[66:67], 12, v[66:67]
	v_lshl_add_u64 v[64:65], v[64:65], 0, v[66:67]
	global_load_dwordx4 v[64:67], v[64:65], off
	v_add_u32_e32 v59, s33, v17
	v_mul_u32_u24_e32 v59, 0x900, v59
	v_mov_b32_e32 v69, v3
	v_lshlrev_b32_e32 v68, 1, v59
	s_mov_b32 s5, s29
	v_lshl_add_u64 v[68:69], s[6:7], 0, v[68:69]
	v_lshl_add_u64 v[68:69], s[4:5], 1, v[68:69]
	v_lshl_add_u64 v[68:69], v[68:69], 0, v[2:3]
	v_add_co_u32_e32 v68, vcc, 0xf80a00, v68
	s_nop 1
	v_addc_co_u32_e32 v69, vcc, 0, v69, vcc
	s_branch .Ltp1_J
.Ltp1_E:
	s_and_b32 s4, s50, 0x1fc0
	s_addk_i32 s4, 0xe600
	s_and_b32 s33, s3, 0x3c0
	s_lshl_b32 s28, s33, 2
	v_or_b32_e32 v60, s4, v1
	v_mov_b32_e32 v61, v3
	v_lshl_add_u64 v[64:65], v[12:13], 0, s[28:29]
	v_lshlrev_b64 v[60:61], 12, v[60:61]
	v_lshl_add_u64 v[60:61], v[64:65], 0, v[60:61]
	v_add_u32_e32 v66, s4, v16
	v_mov_b32_e32 v67, v3
	global_load_dwordx4 v[60:63], v[60:61], off
	v_lshlrev_b64 v[66:67], 12, v[66:67]
	v_lshl_add_u64 v[64:65], v[64:65], 0, v[66:67]
	global_load_dwordx4 v[64:67], v[64:65], off
	v_add_u32_e32 v59, s33, v17
	v_mul_u32_u24_e32 v59, 0x900, v59
	v_mov_b32_e32 v69, v3
	v_lshlrev_b32_e32 v68, 1, v59
	s_mov_b32 s5, s29
	v_lshl_add_u64 v[68:69], s[46:47], 0, v[68:69]
	v_lshl_add_u64 v[68:69], s[4:5], 1, v[68:69]
	v_lshl_add_u64 v[68:69], v[68:69], 0, v[2:3]
	s_branch .Ltp1_J
.Ltp1_F:
	s_mul_hi_i32 s4, s53, 0x4ec4ec4f
	s_lshr_b32 s5, s4, 31
	s_ashr_i32 s4, s4, 5
	s_add_i32 s5, s4, s5
	s_lshl_b32 s4, s5, 6
	s_mulk_i32 s5, 0xe600
	s_add_i32 s44, s3, s5
	s_ashr_i32 s45, s44, 31
	v_lshl_add_u64 v[64:65], s[44:45], 2, v[14:15]
	v_or_b32_e32 v59, s4, v1
	v_mad_i64_i32 v[60:61], s[48:49], v59, s52, v[64:65]
	global_load_dwordx4 v[60:63], v[60:61], off
	v_add_u32_e32 v59, s4, v16
	v_mad_i64_i32 v[64:65], s[48:49], v59, s52, v[64:65]
	global_load_dwordx4 v[64:67], v[64:65], off
	v_add_u32_e32 v68, s44, v17
	v_ashrrev_i32_e32 v69, 31, v68
	v_lshlrev_b64 v[68:69], 11, v[68:69]
	s_ashr_i32 s5, s4, 31
	v_lshl_add_u64 v[68:69], s[6:7], 0, v[68:69]
	v_lshl_add_u64 v[68:69], s[4:5], 1, v[68:69]
	v_lshl_add_u64 v[68:69], v[68:69], 0, v[2:3]
.Ltp1_J:
	s_waitcnt vmcnt(2)
	ds_write2_b32 v18, v24, v25 offset1:1
	ds_write2_b32 v18, v26, v27 offset0:2 offset1:3
	ds_write2_b32 v19, v28, v29 offset1:1
	ds_write2_b32 v20, v30, v31 offset1:1
	s_waitcnt lgkmcnt(0)
	s_barrier
	ds_read2_b32 v[24:25], v21 offset1:65
	ds_read2_b32 v[26:27], v21 offset0:130 offset1:195
	ds_read2_b32 v[28:29], v22 offset0:4 offset1:69
	ds_read2_b32 v[30:31], v22 offset0:134 offset1:199
	s_waitcnt lgkmcnt(3)
	v_cvt_pk_bf16_f32 v24, v24, v25
	s_waitcnt lgkmcnt(2)
	v_cvt_pk_bf16_f32 v25, v26, v27
	s_waitcnt lgkmcnt(1)
	v_cvt_pk_bf16_f32 v26, v28, v29
	s_waitcnt lgkmcnt(0)
	v_cvt_pk_bf16_f32 v27, v30, v31
	global_store_dwordx4 v[32:33], v[24:27], off
	s_barrier
.Ltp_loop:
	s_add_i32 s53, s53, s38
	s_add_i32 s3, s3, s39
	s_add_i32 s50, s50, s51
	s_cmpk_gt_i32 s53, 0x11ff
	s_cbranch_scc1 .Ltp_endB
	s_cmpk_gt_i32 s53, 0x67f
	s_cbranch_scc0 .Ltp2_F
	s_cmpk_gt_u32 s53, 0x7bf
	s_cbranch_scc0 .Ltp2_E
	s_cmpk_gt_u32 s53, 0x8bf
	s_cbranch_scc0 .Ltp2_D
	s_cmpk_gt_u32 s53, 0x9bf
	s_cbranch_scc0 .Ltp2_C
	s_cmpk_gt_u32 s53, 0xf3f
	s_cbranch_scc0 .Ltp2_B
	s_and_b32 s4, s50, 0x7fffffc0
	s_addk_i32 s4, 0xc300
	s_and_b32 s33, s3, 0x3c0
	s_lshl_b32 s28, s33, 2
	v_or_b32_e32 v24, s4, v1
	v_mov_b32_e32 v25, v3
	v_lshl_add_u64 v[28:29], v[4:5], 0, s[28:29]
	v_lshlrev_b64 v[24:25], 12, v[24:25]
	v_lshl_add_u64 v[24:25], v[28:29], 0, v[24:25]
	v_add_u32_e32 v30, s4, v16
	v_mov_b32_e32 v31, v3
	global_load_dwordx4 v[24:27], v[24:25], off
	v_lshlrev_b64 v[30:31], 12, v[30:31]
	v_lshl_add_u64 v[28:29], v[28:29], 0, v[30:31]
	global_load_dwordx4 v[28:31], v[28:29], off
	v_add_u32_e32 v23, s33, v17
	v_mul_u32_u24_e32 v23, 0xb00, v23
	v_mov_b32_e32 v33, v3
	v_lshlrev_b32_e32 v32, 1, v23
	s_mov_b32 s5, s29
	v_lshl_add_u64 v[32:33], s[30:31], 0, v[32:33]
	v_lshl_add_u64 v[32:33], s[4:5], 1, v[32:33]
	v_lshl_add_u64 v[32:33], v[32:33], 0, v[2:3]
	s_branch .Ltp2_J

.Ltp2_J:
	s_waitcnt vmcnt(3)
	ds_write2_b32 v18, v60, v61 offset1:1
	ds_write2_b32 v18, v62, v63 offset0:2 offset1:3
	ds_write2_b32 v19, v64, v65 offset1:1
	ds_write2_b32 v20, v66, v67 offset1:1
	s_waitcnt lgkmcnt(0)
	s_barrier
	ds_read2_b32 v[60:61], v21 offset1:65
	ds_read2_b32 v[62:63], v21 offset0:130 offset1:195
	ds_read2_b32 v[64:65], v22 offset0:4 offset1:69
	ds_read2_b32 v[66:67], v22 offset0:134 offset1:199
	s_waitcnt lgkmcnt(3)
	v_cvt_pk_bf16_f32 v60, v60, v61
	s_waitcnt lgkmcnt(2)
	v_cvt_pk_bf16_f32 v61, v62, v63
	s_waitcnt lgkmcnt(1)
	v_cvt_pk_bf16_f32 v62, v64, v65
	s_waitcnt lgkmcnt(0)
	v_cvt_pk_bf16_f32 v63, v66, v67
	global_store_dwordx4 v[68:69], v[60:63], off
	s_barrier
	s_add_i32 s53, s53, s38
	s_add_i32 s3, s3, s39
	s_add_i32 s50, s50, s51
	s_cmpk_gt_i32 s53, 0x11ff
	s_cbranch_scc1 .Ltp_endA
	s_cmpk_gt_i32 s53, 0x67f
	s_cbranch_scc0 .Ltp3_F
	s_cmpk_gt_u32 s53, 0x7bf
	s_cbranch_scc0 .Ltp3_E
	s_cmpk_gt_u32 s53, 0x8bf
	s_cbranch_scc0 .Ltp3_D
	s_cmpk_gt_u32 s53, 0x9bf
	s_cbranch_scc0 .Ltp3_C
	s_cmpk_gt_u32 s53, 0xf3f
	s_cbranch_scc0 .Ltp3_B
	s_and_b32 s4, s50, 0x7fffffc0
	s_addk_i32 s4, 0xc300
	s_and_b32 s33, s3, 0x3c0
	s_lshl_b32 s28, s33, 2
	v_or_b32_e32 v60, s4, v1
	v_mov_b32_e32 v61, v3
	v_lshl_add_u64 v[64:65], v[4:5], 0, s[28:29]
	v_lshlrev_b64 v[60:61], 12, v[60:61]
	v_lshl_add_u64 v[60:61], v[64:65], 0, v[60:61]
	v_add_u32_e32 v66, s4, v16
	v_mov_b32_e32 v67, v3
	global_load_dwordx4 v[60:63], v[60:61], off
	v_lshlrev_b64 v[66:67], 12, v[66:67]
	v_lshl_add_u64 v[64:65], v[64:65], 0, v[66:67]
	global_load_dwordx4 v[64:67], v[64:65], off
	v_add_u32_e32 v59, s33, v17
	v_mul_u32_u24_e32 v59, 0xb00, v59
	v_mov_b32_e32 v69, v3
	v_lshlrev_b32_e32 v68, 1, v59
	s_mov_b32 s5, s29
	v_lshl_add_u64 v[68:69], s[30:31], 0, v[68:69]
	v_lshl_add_u64 v[68:69], s[4:5], 1, v[68:69]
	v_lshl_add_u64 v[68:69], v[68:69], 0, v[2:3]
	s_branch .Ltp3_J

.Ltp3_J:
	s_waitcnt vmcnt(3)
	ds_write2_b32 v18, v24, v25 offset1:1
	ds_write2_b32 v18, v26, v27 offset0:2 offset1:3
	ds_write2_b32 v19, v28, v29 offset1:1
	ds_write2_b32 v20, v30, v31 offset1:1
	s_waitcnt lgkmcnt(0)
	s_barrier
	ds_read2_b32 v[24:25], v21 offset1:65
	ds_read2_b32 v[26:27], v21 offset0:130 offset1:195
	ds_read2_b32 v[28:29], v22 offset0:4 offset1:69
	ds_read2_b32 v[30:31], v22 offset0:134 offset1:199
	s_waitcnt lgkmcnt(3)
	v_cvt_pk_bf16_f32 v24, v24, v25
	s_waitcnt lgkmcnt(2)
	v_cvt_pk_bf16_f32 v25, v26, v27
	s_waitcnt lgkmcnt(1)
	v_cvt_pk_bf16_f32 v26, v28, v29
	s_waitcnt lgkmcnt(0)
	v_cvt_pk_bf16_f32 v27, v30, v31
	global_store_dwordx4 v[32:33], v[24:27], off
	s_barrier
	s_branch .Ltp_loop
.Ltp_endA:
	s_waitcnt vmcnt(0)
	ds_write2_b32 v18, v24, v25 offset1:1
	ds_write2_b32 v18, v26, v27 offset0:2 offset1:3
	ds_write2_b32 v19, v28, v29 offset1:1
	ds_write2_b32 v20, v30, v31 offset1:1
	s_waitcnt lgkmcnt(0)
	s_barrier
	ds_read2_b32 v[24:25], v21 offset1:65
	ds_read2_b32 v[26:27], v21 offset0:130 offset1:195
	ds_read2_b32 v[28:29], v22 offset0:4 offset1:69
	ds_read2_b32 v[30:31], v22 offset0:134 offset1:199
	s_waitcnt lgkmcnt(3)
	v_cvt_pk_bf16_f32 v24, v24, v25
	s_waitcnt lgkmcnt(2)
	v_cvt_pk_bf16_f32 v25, v26, v27
	s_waitcnt lgkmcnt(1)
	v_cvt_pk_bf16_f32 v26, v28, v29
	s_waitcnt lgkmcnt(0)
	v_cvt_pk_bf16_f32 v27, v30, v31
	global_store_dwordx4 v[32:33], v[24:27], off
	s_barrier
	s_branch .LBB0_28
.Ltp_endB:
	s_waitcnt vmcnt(0)
	ds_write2_b32 v18, v60, v61 offset1:1
	ds_write2_b32 v18, v62, v63 offset0:2 offset1:3
	ds_write2_b32 v19, v64, v65 offset1:1
	ds_write2_b32 v20, v66, v67 offset1:1
	s_waitcnt lgkmcnt(0)
	s_barrier
	ds_read2_b32 v[60:61], v21 offset1:65
	ds_read2_b32 v[62:63], v21 offset0:130 offset1:195
	ds_read2_b32 v[64:65], v22 offset0:4 offset1:69
	ds_read2_b32 v[66:67], v22 offset0:134 offset1:199
	s_waitcnt lgkmcnt(3)
	v_cvt_pk_bf16_f32 v60, v60, v61
	s_waitcnt lgkmcnt(2)
	v_cvt_pk_bf16_f32 v61, v62, v63
	s_waitcnt lgkmcnt(1)
	v_cvt_pk_bf16_f32 v62, v64, v65
	s_waitcnt lgkmcnt(0)
	v_cvt_pk_bf16_f32 v63, v66, v67
	global_store_dwordx4 v[68:69], v[60:63], off
	s_barrier
